# MLA odd steps: the first two K-fragment LDS reads issued right after the step barrier, ahead of the next tile's LDS writes
# baseline (speedup 1.0000x reference)
; #define LOADT(RK, RV, tt) do { const char* kb_ = (const char*)(Kb + (size_t)(tt) * (64 * 192)); const char* vb_ = (const char*)(Vb + (size_t)(tt) * 64); \
;     _Pragma("unroll") for (int i = 0; i < 3; ++i) RK[i] = *(const u32x4*)(kb_ + i * 8192 + kgo); \
;     _Pragma("unroll") for (int i = 0; i < 2; ++i) RV[i] = *(const u32x4*)(vb_ + (size_t)i * (64 * S * 2) + vgo); } while (0)
; #define STORET(RK, RV, kbuf, vbuf) do { \
;     _Pragma("unroll") for (int i = 0; i < 3; ++i) *(LAS u32x4*)(L + (kbuf) * (2 * MLA_KS) + kds[i]) = RK[i]; \
;     _Pragma("unroll") for (int i = 0; i < 2; ++i) { LAS u32x2* d_ = (LAS u32x2*)(L + (vbuf) * (2 * MLA_VS) + vds + i * (64 * 36)); d_[0] = (u32x2){RV[i].x, RV[i].y}; d_[1] = (u32x2){RV[i].z, RV[i].w}; } } while (0)
; __device__ __forceinline__ void mla_unit(LAS unsigned char* lds, int bh, int x, const bf16* QM, const bf16* KM, const bf16* VMT, bf16* OUT, ssq_t* SSo, int tid, int lane, int wave) {
;     ...
;         __syncthreads();
;         if (t + 1 < T) STORET(rk0, rv0, 0, (vb == 2) ? 0 : vb + 1);
;         if (t + 3 < T) LOADT(rk0, rv0, t + 3);
;         { const int vbp = (vb == 0) ? 2 : vb - 1; PHASE_A(t, 1, true); PHASE_B(t, vbp, true); vb = (vb == 2) ? 0 : vb + 1; }
.LBB0_1296:
	s_mul_i32 s16, s18, 0x2400
	s_add_i32 s14, s16, 0x2400
	s_cmp_eq_u32 s18, 2
	s_cselect_b64 s[10:11], -1, 0
	s_and_b64 s[8:9], s[10:11], exec
	s_cselect_b32 s8, 0, s14
	s_add_i32 s49, s4, 2
	s_cmp_ge_u32 s49, s45
	v_lshl_add_u32 v82, s8, 1, v214
	s_cselect_b64 s[8:9], -1, 0
	v_add_u32_e32 v83, 0xc800, v82
	v_add_u32_e32 v82, 0xda00, v82
	s_and_b64 vcc, exec, s[8:9]
	v_lshl_add_u64 v[192:193], v[188:189], 0, s[2:3]
	v_lshl_add_u64 v[190:191], v[186:187], 0, s[2:3]
	s_barrier
	ds_read_b128 v[228:231], v209 offset:25600
	ds_read_b128 v[232:235], v209 offset:25632
	s_waitcnt vmcnt(4)
	ds_write_b128 v211, v[124:127]
	s_waitcnt vmcnt(3)
	ds_write_b128 v212, v[128:131]
	s_waitcnt vmcnt(2)
	ds_write_b128 v213, v[132:135]
	s_waitcnt vmcnt(1)
	ds_write2_b64 v83, v[136:137], v[138:139] offset1:1
	s_waitcnt vmcnt(0)
	ds_write2_b64 v82, v[144:145], v[146:147] offset1:1
	s_cbranch_vccnz .LBB0_1298
	v_add_co_u32_e32 v82, vcc, 0x9d18000, v192
	s_nop 1
	v_addc_co_u32_e32 v83, vcc, 0, v193, vcc
	v_add_co_u32_e32 v84, vcc, 0x9d1a000, v192
	s_nop 1
	v_addc_co_u32_e32 v85, vcc, 0, v193, vcc
	global_load_dwordx4 v[124:127], v[82:83], off
	global_load_dwordx4 v[128:131], v[84:85], off
	v_add_co_u32_e32 v82, vcc, 0x9d1c000, v192
	s_nop 1
	v_addc_co_u32_e32 v83, vcc, 0, v193, vcc
	global_load_dwordx4 v[132:135], v[82:83], off
	v_add_co_u32_e32 v82, vcc, 0xb500000, v190
	s_nop 1
	v_addc_co_u32_e32 v83, vcc, 0, v191, vcc
	v_add_co_u32_e32 v84, vcc, 0xb600000, v190
	s_nop 1
	v_addc_co_u32_e32 v85, vcc, 0, v191, vcc
	global_load_dwordx4 v[136:139], v[82:83], off offset:512
	global_load_dwordx4 v[144:147], v[84:85], off offset:512
.LBB0_1298:
	v_xor_b32_e32 v82, 0x80000000, v1
	s_add_i32 s14, s4, -1
	v_mov_b32_e32 v83, v82
	v_mov_b32_e32 v84, v82
	v_mov_b32_e32 v85, v82
	v_mov_b32_e32 v86, v82
	v_mov_b32_e32 v87, v82
	v_mov_b32_e32 v88, v82
	v_mov_b32_e32 v89, v82
	v_mov_b32_e32 v90, v82
	v_mov_b32_e32 v91, v82
	v_mov_b32_e32 v92, v82
	v_mov_b32_e32 v93, v82
	v_mov_b32_e32 v94, v82
	v_mov_b32_e32 v95, v82
	v_mov_b32_e32 v96, v82
	v_mov_b32_e32 v97, v82
	s_waitcnt lgkmcnt(1)
	s_nop 0
	v_mfma_f32_32x32x16_bf16 v[82:97], v[228:231], v[120:123], v[82:97]
	ds_read_b128 v[236:239], v209 offset:25664
	s_waitcnt lgkmcnt(1)
	v_mfma_f32_32x32x16_bf16 v[82:97], v[232:235], v[116:119], v[82:97]
	ds_read_b128 v[228:231], v209 offset:25696
	s_waitcnt lgkmcnt(1)
	v_mfma_f32_32x32x16_bf16 v[82:97], v[236:239], v[112:115], v[82:97]
	ds_read_b128 v[232:235], v209 offset:25728
	s_waitcnt lgkmcnt(1)
	v_mfma_f32_32x32x16_bf16 v[82:97], v[228:231], v[108:111], v[82:97]
	ds_read_b128 v[236:239], v209 offset:25760
	s_waitcnt lgkmcnt(1)
	v_mfma_f32_32x32x16_bf16 v[82:97], v[232:235], v[104:107], v[82:97]
	ds_read_b128 v[228:231], v209 offset:25792
	ds_read_b128 v[240:243], v208 offset:192
	s_waitcnt lgkmcnt(2)
	v_mfma_f32_32x32x16_bf16 v[82:97], v[236:239], v[100:103], v[82:97]
	ds_read_b128 v[232:235], v209 offset:25824
	ds_read_b128 v[244:247], v208 offset:224
	s_waitcnt lgkmcnt(2)
	v_mfma_f32_32x32x16_bf16 v[82:97], v[228:231], v[240:243], v[82:97]
	ds_read_b128 v[236:239], v209 offset:25856
	ds_read_b128 v[248:251], v208 offset:256
	s_waitcnt lgkmcnt(2)
	v_mfma_f32_32x32x16_bf16 v[82:97], v[232:235], v[244:247], v[82:97]
	ds_read_b128 v[228:231], v209 offset:25888
	ds_read_b128 v[240:243], v208 offset:288
	s_waitcnt lgkmcnt(2)
	v_mfma_f32_32x32x16_bf16 v[82:97], v[236:239], v[248:251], v[82:97]
	ds_read_b128 v[232:235], v209 offset:25920
	ds_read_b128 v[244:247], v208 offset:320
	s_waitcnt lgkmcnt(2)
	v_mfma_f32_32x32x16_bf16 v[82:97], v[228:231], v[240:243], v[82:97]
	ds_read_b128 v[236:239], v209 offset:25952
	ds_read_b128 v[248:251], v208 offset:352
	s_waitcnt lgkmcnt(2)
	v_mfma_f32_32x32x16_bf16 v[82:97], v[232:235], v[244:247], v[82:97]
	s_waitcnt lgkmcnt(0)
	v_mfma_f32_32x32x16_bf16 v[82:97], v[236:239], v[248:251], v[82:97]
	s_cmp_lt_u32 s14, s44
	s_cselect_b64 s[14:15], -1, 0
	s_and_b64 vcc, exec, s[14:15]
	s_cbranch_vccnz .LBB0_1300
	s_add_i32 s17, s48, 0xffffffa5
	v_cmp_lt_i32_e32 vcc, s17, v224
	s_nop 5
	v_cndmask_b32_e32 v83, v206, v83, vcc
	v_cmp_le_i32_e32 vcc, s17, v224
	s_add_i32 s17, s48, 0xffffffa7
	s_nop 0
	v_cndmask_b32_e32 v82, v206, v82, vcc
	v_cmp_le_i32_e32 vcc, s17, v224
	s_add_i32 s17, s48, 0xffffffa8
	s_nop 0
	v_cndmask_b32_e32 v84, v206, v84, vcc
	v_cmp_le_i32_e32 vcc, s17, v224
	s_add_i32 s17, s48, 0xffffffad
	s_nop 0
	v_cndmask_b32_e32 v85, v206, v85, vcc
	v_cmp_le_i32_e32 vcc, s17, v224
	s_add_i32 s17, s48, 0xffffffae
	s_nop 0
	v_cndmask_b32_e32 v86, v206, v86, vcc
	v_cmp_le_i32_e32 vcc, s17, v224
	s_add_i32 s17, s48, 0xffffffaf
	s_nop 0
	v_cndmask_b32_e32 v87, v206, v87, vcc
	v_cmp_le_i32_e32 vcc, s17, v224
	s_add_i32 s17, s48, 0xffffffb0
	s_nop 0
	v_cndmask_b32_e32 v88, v206, v88, vcc
	v_cmp_le_i32_e32 vcc, s17, v224
	s_add_i32 s17, s48, 0xffffffb5
	s_nop 0
	v_cndmask_b32_e32 v89, v206, v89, vcc
	v_cmp_le_i32_e32 vcc, s17, v224
	s_add_i32 s17, s48, 0xffffffb6
	s_nop 0
	v_cndmask_b32_e32 v90, v206, v90, vcc
	v_cmp_le_i32_e32 vcc, s17, v224
	s_add_i32 s17, s48, 0xffffffb7
	s_nop 0
	v_cndmask_b32_e32 v91, v206, v91, vcc
	v_cmp_le_i32_e32 vcc, s17, v224
	s_add_i32 s17, s48, 0xffffffb8
	s_nop 0
	v_cndmask_b32_e32 v92, v206, v92, vcc
	v_cmp_le_i32_e32 vcc, s17, v224
	s_add_i32 s17, s48, 0xffffffbd
	s_nop 0
	v_cndmask_b32_e32 v93, v206, v93, vcc
	v_cmp_le_i32_e32 vcc, s17, v224
	s_add_i32 s17, s48, 0xffffffbe
	s_nop 0
	v_cndmask_b32_e32 v94, v206, v94, vcc
	v_cmp_le_i32_e32 vcc, s17, v224
	s_add_i32 s17, s48, 0xffffffbf
	s_nop 0
	v_cndmask_b32_e32 v95, v206, v95, vcc
	v_cmp_le_i32_e32 vcc, s17, v224
	s_sub_i32 s17, s48, 64
	s_nop 0
	v_cndmask_b32_e32 v96, v206, v96, vcc
	v_cmp_le_i32_e32 vcc, s17, v224
	s_nop 1
	v_cndmask_b32_e32 v97, v206, v97, vcc
